# v14: out-projection epilogue de-serialised (16 residual loads requested up front, counted vmcnt)
# speedup vs baseline: 1.0474x; 1.0057x over previous
.LBB0_14:
	v_ashrrev_i32_e32 v0, 12, v0
	v_add_u32_e32 v0, 1, v0
	v_cndmask_b32_e64 v0, v0, 0, s[8:9]
	s_load_dwordx2 s[8:9], s[0:1], 0xe8
	s_mul_i32 s10, s74, 9
	v_add_u32_e32 v0, s10, v0
	v_mov_b32_e32 v121, v1
	v_mov_b32_e32 v123, v1
	s_waitcnt lgkmcnt(0)
	v_lshl_add_u64 v[68:69], s[8:9], 0, v[70:71]
	s_load_dwordx2 s[8:9], s[0:1], 0x188
	s_mov_b64 s[24:25], -1
	s_waitcnt lgkmcnt(0)
	v_mov_b64_e32 v[70:71], s[8:9]
	v_mad_i64_i32 v[70:71], s[8:9], v0, s87, v[70:71]
	v_lshl_add_u64 v[70:71], s[22:23], 2, v[70:71]
	v_lshl_add_u64 v[70:71], v[70:71], 0, v[120:121]
	v_lshl_add_u64 v[70:71], v[70:71], 0, v[122:123]
	s_mov_b64 s[8:9], 0x2000
	v_lshl_add_u64 v[72:73], v[70:71], 0, s[8:9]
	s_movk_i32 s8, 0x2000
	v_add_co_u32_e32 v70, vcc, s8, v70
	s_nop 1
	v_addc_co_u32_e32 v71, vcc, 0, v71, vcc
	global_load_dword v0, v[70:71], off
	s_nop 0
	global_load_dword v72, v[72:73], off offset:64
	v_mov_b32_e32 v71, s23
	v_or_b32_e32 v70, s22, v86
	s_and_b64 vcc, exec, s[20:21]
	s_waitcnt vmcnt(0)
	v_lshl_add_u64 v[152:153], v[70:71], 0, v[88:89]
	v_lshlrev_b64 v[152:153], 2, v[152:153]
	v_lshl_add_u64 v[152:153], v[66:67], 0, v[152:153]
	global_load_dwordx4 v[152:155], v[152:153], off
	v_lshl_add_u64 v[156:157], v[70:71], 0, v[90:91]
	v_lshlrev_b64 v[156:157], 2, v[156:157]
	v_lshl_add_u64 v[156:157], v[66:67], 0, v[156:157]
	global_load_dwordx4 v[156:159], v[156:157], off
	v_lshl_add_u64 v[160:161], v[70:71], 0, v[92:93]
	v_lshlrev_b64 v[160:161], 2, v[160:161]
	v_lshl_add_u64 v[160:161], v[66:67], 0, v[160:161]
	global_load_dwordx4 v[160:163], v[160:161], off
	v_lshl_add_u64 v[164:165], v[70:71], 0, v[94:95]
	v_lshlrev_b64 v[164:165], 2, v[164:165]
	v_lshl_add_u64 v[164:165], v[66:67], 0, v[164:165]
	global_load_dwordx4 v[164:167], v[164:165], off
	v_lshl_add_u64 v[168:169], v[70:71], 0, v[96:97]
	v_lshlrev_b64 v[168:169], 2, v[168:169]
	v_lshl_add_u64 v[168:169], v[66:67], 0, v[168:169]
	global_load_dwordx4 v[168:171], v[168:169], off
	v_lshl_add_u64 v[172:173], v[70:71], 0, v[98:99]
	v_lshlrev_b64 v[172:173], 2, v[172:173]
	v_lshl_add_u64 v[172:173], v[66:67], 0, v[172:173]
	global_load_dwordx4 v[172:175], v[172:173], off
	v_lshl_add_u64 v[176:177], v[70:71], 0, v[100:101]
	v_lshlrev_b64 v[176:177], 2, v[176:177]
	v_lshl_add_u64 v[176:177], v[66:67], 0, v[176:177]
	global_load_dwordx4 v[176:179], v[176:177], off
	v_lshl_add_u64 v[180:181], v[70:71], 0, v[102:103]
	v_lshlrev_b64 v[180:181], 2, v[180:181]
	v_lshl_add_u64 v[180:181], v[66:67], 0, v[180:181]
	global_load_dwordx4 v[180:183], v[180:181], off
	v_lshl_add_u64 v[184:185], v[70:71], 0, v[104:105]
	v_lshlrev_b64 v[184:185], 2, v[184:185]
	v_lshl_add_u64 v[184:185], v[66:67], 0, v[184:185]
	global_load_dwordx4 v[184:187], v[184:185], off
	v_lshl_add_u64 v[188:189], v[70:71], 0, v[106:107]
	v_lshlrev_b64 v[188:189], 2, v[188:189]
	v_lshl_add_u64 v[188:189], v[66:67], 0, v[188:189]
	global_load_dwordx4 v[188:191], v[188:189], off
	v_lshl_add_u64 v[192:193], v[70:71], 0, v[108:109]
	v_lshlrev_b64 v[192:193], 2, v[192:193]
	v_lshl_add_u64 v[192:193], v[66:67], 0, v[192:193]
	global_load_dwordx4 v[192:195], v[192:193], off
	v_lshl_add_u64 v[196:197], v[70:71], 0, v[110:111]
	v_lshlrev_b64 v[196:197], 2, v[196:197]
	v_lshl_add_u64 v[196:197], v[66:67], 0, v[196:197]
	global_load_dwordx4 v[196:199], v[196:197], off
	v_lshl_add_u64 v[200:201], v[70:71], 0, v[112:113]
	v_lshlrev_b64 v[200:201], 2, v[200:201]
	v_lshl_add_u64 v[200:201], v[66:67], 0, v[200:201]
	global_load_dwordx4 v[200:203], v[200:201], off
	v_lshl_add_u64 v[204:205], v[70:71], 0, v[114:115]
	v_lshlrev_b64 v[204:205], 2, v[204:205]
	v_lshl_add_u64 v[204:205], v[66:67], 0, v[204:205]
	global_load_dwordx4 v[204:207], v[204:205], off
	v_lshl_add_u64 v[208:209], v[70:71], 0, v[116:117]
	v_lshlrev_b64 v[208:209], 2, v[208:209]
	v_lshl_add_u64 v[208:209], v[66:67], 0, v[208:209]
	global_load_dwordx4 v[208:211], v[208:209], off
	v_lshl_add_u64 v[74:75], v[70:71], 0, v[118:119]
	v_lshlrev_b64 v[74:75], 2, v[74:75]
	v_lshl_add_u64 v[74:75], v[66:67], 0, v[74:75]
	global_load_dwordx4 v[74:77], v[74:75], off
	v_mul_f32_e32 v62, v62, v0
	v_mul_f32_e32 v58, v58, v72
	ds_write2_b32 v136, v62, v58 offset1:16
	v_mul_f32_e32 v58, v63, v0
	v_mul_f32_e32 v59, v59, v72
	ds_write2_b32 v136, v58, v59 offset0:36 offset1:52
	v_mul_f32_e32 v58, v64, v0
	v_mul_f32_e32 v59, v60, v72
	ds_write2_b32 v136, v58, v59 offset0:72 offset1:88
	v_mul_f32_e32 v58, v65, v0
	v_mul_f32_e32 v59, v61, v72
	ds_write2_b32 v136, v58, v59 offset0:108 offset1:124
	v_mul_f32_e32 v54, v54, v0
	v_mul_f32_e32 v58, v50, v72
	v_add_u32_e32 v50, 0x800, v136
	ds_write2_b32 v50, v54, v58 offset0:64 offset1:80
	v_mul_f32_e32 v54, v55, v0
	v_mul_f32_e32 v51, v51, v72
	ds_write2_b32 v50, v54, v51 offset0:100 offset1:116
	v_mul_f32_e32 v51, v56, v0
	v_mul_f32_e32 v52, v52, v72
	ds_write2_b32 v50, v51, v52 offset0:136 offset1:152
	v_mul_f32_e32 v51, v57, v0
	v_mul_f32_e32 v52, v53, v72
	v_lshl_add_u64 v[56:57], v[70:71], 0, v[88:89]
	ds_write2_b32 v50, v51, v52 offset0:172 offset1:188
	v_lshlrev_b64 v[60:61], 2, v[56:57]
	s_waitcnt lgkmcnt(0)
	v_lshl_add_u64 v[56:57], v[66:67], 0, v[60:61]
	ds_read_b128 v[52:55], v137
	v_mul_f32_e32 v46, v46, v0
	v_mul_f32_e32 v42, v42, v72
	v_mul_f32_e32 v38, v38, v0
	v_mul_f32_e32 v34, v34, v72
	v_mul_f32_e32 v43, v43, v72
	v_mul_f32_e32 v35, v35, v72
	v_mul_f32_e32 v30, v30, v0
	v_mul_f32_e32 v26, v26, v72
	v_mul_f32_e32 v22, v22, v0
	v_mul_f32_e32 v18, v18, v72
	v_mul_f32_e32 v27, v27, v72
	v_mul_f32_e32 v19, v19, v72
	v_mul_f32_e32 v14, v14, v0
	v_mul_f32_e32 v10, v10, v72
	v_mul_f32_e32 v6, v6, v0
	v_mul_f32_e32 v2, v2, v72
	v_mul_f32_e32 v11, v11, v72
	v_mul_f32_e32 v3, v3, v72
	s_waitcnt vmcnt(15) lgkmcnt(0)
	v_pk_fma_f32 v[54:55], v[154:155], s[98:99], v[54:55] op_sel_hi:[1,0,1]
	v_pk_fma_f32 v[52:53], v[152:153], s[98:99], v[52:53] op_sel_hi:[1,0,1]
	v_lshl_add_u64 v[56:57], v[68:69], 0, v[60:61]
	global_store_dwordx4 v[56:57], v[52:55], off sc0 sc1
	v_lshl_add_u64 v[56:57], v[70:71], 0, v[90:91]
	v_lshlrev_b64 v[60:61], 2, v[56:57]
	v_lshl_add_u64 v[56:57], v[66:67], 0, v[60:61]
	ds_read_b128 v[52:55], v138
	s_waitcnt vmcnt(15) lgkmcnt(0)
	v_pk_fma_f32 v[54:55], v[158:159], s[98:99], v[54:55] op_sel_hi:[1,0,1]
	v_pk_fma_f32 v[52:53], v[156:157], s[98:99], v[52:53] op_sel_hi:[1,0,1]
	v_lshl_add_u64 v[56:57], v[68:69], 0, v[60:61]
	global_store_dwordx4 v[56:57], v[52:55], off sc0 sc1
	v_lshl_add_u64 v[56:57], v[70:71], 0, v[92:93]
	v_lshlrev_b64 v[60:61], 2, v[56:57]
	v_lshl_add_u64 v[56:57], v[66:67], 0, v[60:61]
	ds_read_b128 v[52:55], v139
	s_waitcnt vmcnt(15) lgkmcnt(0)
	v_pk_fma_f32 v[54:55], v[162:163], s[98:99], v[54:55] op_sel_hi:[1,0,1]
	v_pk_fma_f32 v[52:53], v[160:161], s[98:99], v[52:53] op_sel_hi:[1,0,1]
	v_lshl_add_u64 v[56:57], v[68:69], 0, v[60:61]
	global_store_dwordx4 v[56:57], v[52:55], off sc0 sc1
	v_lshl_add_u64 v[56:57], v[70:71], 0, v[94:95]
	v_lshlrev_b64 v[60:61], 2, v[56:57]
	v_lshl_add_u64 v[56:57], v[66:67], 0, v[60:61]
	ds_read_b128 v[52:55], v140
	s_waitcnt vmcnt(15) lgkmcnt(0)
	v_pk_fma_f32 v[54:55], v[166:167], s[98:99], v[54:55] op_sel_hi:[1,0,1]
	v_pk_fma_f32 v[52:53], v[164:165], s[98:99], v[52:53] op_sel_hi:[1,0,1]
	v_lshl_add_u64 v[56:57], v[68:69], 0, v[60:61]
	global_store_dwordx4 v[56:57], v[52:55], off sc0 sc1
	s_waitcnt lgkmcnt(0)
	ds_write2_b32 v136, v46, v42 offset1:16
	v_mul_f32_e32 v42, v47, v0
	ds_write2_b32 v50, v38, v34 offset0:64 offset1:80
	v_mul_f32_e32 v34, v39, v0
	ds_write2_b32 v136, v42, v43 offset0:36 offset1:52
	v_mul_f32_e32 v42, v48, v0
	v_mul_f32_e32 v43, v44, v72
	ds_write2_b32 v50, v34, v35 offset0:100 offset1:116
	v_mul_f32_e32 v34, v40, v0
	v_mul_f32_e32 v35, v36, v72
	ds_write2_b32 v136, v42, v43 offset0:72 offset1:88
	v_mul_f32_e32 v42, v49, v0
	v_mul_f32_e32 v43, v45, v72
	ds_write2_b32 v50, v34, v35 offset0:136 offset1:152
	v_mul_f32_e32 v34, v41, v0
	v_mul_f32_e32 v35, v37, v72
	v_lshl_add_u64 v[38:39], v[70:71], 0, v[96:97]
	ds_write2_b32 v136, v42, v43 offset0:108 offset1:124
	ds_write2_b32 v50, v34, v35 offset0:172 offset1:188
	v_lshlrev_b64 v[42:43], 2, v[38:39]
	s_waitcnt lgkmcnt(0)
	v_lshl_add_u64 v[38:39], v[66:67], 0, v[42:43]
	ds_read_b128 v[34:37], v137
	s_waitcnt vmcnt(15) lgkmcnt(0)
	v_pk_fma_f32 v[36:37], v[170:171], s[98:99], v[36:37] op_sel_hi:[1,0,1]
	v_pk_fma_f32 v[34:35], v[168:169], s[98:99], v[34:35] op_sel_hi:[1,0,1]
	v_lshl_add_u64 v[38:39], v[68:69], 0, v[42:43]
	global_store_dwordx4 v[38:39], v[34:37], off sc0 sc1
	v_lshl_add_u64 v[38:39], v[70:71], 0, v[98:99]
	v_lshlrev_b64 v[42:43], 2, v[38:39]
	v_lshl_add_u64 v[38:39], v[66:67], 0, v[42:43]
	ds_read_b128 v[34:37], v138
	s_waitcnt vmcnt(15) lgkmcnt(0)
	v_pk_fma_f32 v[36:37], v[174:175], s[98:99], v[36:37] op_sel_hi:[1,0,1]
	v_pk_fma_f32 v[34:35], v[172:173], s[98:99], v[34:35] op_sel_hi:[1,0,1]
	v_lshl_add_u64 v[38:39], v[68:69], 0, v[42:43]
	global_store_dwordx4 v[38:39], v[34:37], off sc0 sc1
	v_lshl_add_u64 v[38:39], v[70:71], 0, v[100:101]
	v_lshlrev_b64 v[42:43], 2, v[38:39]
	v_lshl_add_u64 v[38:39], v[66:67], 0, v[42:43]
	ds_read_b128 v[34:37], v139
	s_waitcnt vmcnt(15) lgkmcnt(0)
	v_pk_fma_f32 v[36:37], v[178:179], s[98:99], v[36:37] op_sel_hi:[1,0,1]
	v_pk_fma_f32 v[34:35], v[176:177], s[98:99], v[34:35] op_sel_hi:[1,0,1]
	v_lshl_add_u64 v[38:39], v[68:69], 0, v[42:43]
	global_store_dwordx4 v[38:39], v[34:37], off sc0 sc1
	v_lshl_add_u64 v[38:39], v[70:71], 0, v[102:103]
	v_lshlrev_b64 v[42:43], 2, v[38:39]
	v_lshl_add_u64 v[38:39], v[66:67], 0, v[42:43]
	ds_read_b128 v[34:37], v140
	s_waitcnt vmcnt(15) lgkmcnt(0)
	v_pk_fma_f32 v[36:37], v[182:183], s[98:99], v[36:37] op_sel_hi:[1,0,1]
	v_pk_fma_f32 v[34:35], v[180:181], s[98:99], v[34:35] op_sel_hi:[1,0,1]
	v_lshl_add_u64 v[38:39], v[68:69], 0, v[42:43]
	global_store_dwordx4 v[38:39], v[34:37], off sc0 sc1
	s_waitcnt lgkmcnt(0)
	ds_write2_b32 v136, v30, v26 offset1:16
	v_mul_f32_e32 v26, v31, v0
	ds_write2_b32 v50, v22, v18 offset0:64 offset1:80
	v_mul_f32_e32 v18, v23, v0
	ds_write2_b32 v136, v26, v27 offset0:36 offset1:52
	v_mul_f32_e32 v26, v32, v0
	v_mul_f32_e32 v27, v28, v72
	ds_write2_b32 v50, v18, v19 offset0:100 offset1:116
	v_mul_f32_e32 v18, v24, v0
	v_mul_f32_e32 v19, v20, v72
	ds_write2_b32 v136, v26, v27 offset0:72 offset1:88
	v_mul_f32_e32 v26, v33, v0
	v_mul_f32_e32 v27, v29, v72
	ds_write2_b32 v50, v18, v19 offset0:136 offset1:152
	v_mul_f32_e32 v18, v25, v0
	v_mul_f32_e32 v19, v21, v72
	v_lshl_add_u64 v[22:23], v[70:71], 0, v[104:105]
	ds_write2_b32 v136, v26, v27 offset0:108 offset1:124
	ds_write2_b32 v50, v18, v19 offset0:172 offset1:188
	v_lshlrev_b64 v[26:27], 2, v[22:23]
	s_waitcnt lgkmcnt(0)
	v_lshl_add_u64 v[22:23], v[66:67], 0, v[26:27]
	ds_read_b128 v[18:21], v137
	s_waitcnt vmcnt(15) lgkmcnt(0)
	v_pk_fma_f32 v[20:21], v[186:187], s[98:99], v[20:21] op_sel_hi:[1,0,1]
	v_pk_fma_f32 v[18:19], v[184:185], s[98:99], v[18:19] op_sel_hi:[1,0,1]
	v_lshl_add_u64 v[22:23], v[68:69], 0, v[26:27]
	global_store_dwordx4 v[22:23], v[18:21], off sc0 sc1
	v_lshl_add_u64 v[22:23], v[70:71], 0, v[106:107]
	v_lshlrev_b64 v[26:27], 2, v[22:23]
	v_lshl_add_u64 v[22:23], v[66:67], 0, v[26:27]
	ds_read_b128 v[18:21], v138
	s_waitcnt vmcnt(15) lgkmcnt(0)
	v_pk_fma_f32 v[20:21], v[190:191], s[98:99], v[20:21] op_sel_hi:[1,0,1]
	v_pk_fma_f32 v[18:19], v[188:189], s[98:99], v[18:19] op_sel_hi:[1,0,1]
	v_lshl_add_u64 v[22:23], v[68:69], 0, v[26:27]
	global_store_dwordx4 v[22:23], v[18:21], off sc0 sc1
	v_lshl_add_u64 v[22:23], v[70:71], 0, v[108:109]
	v_lshlrev_b64 v[26:27], 2, v[22:23]
	v_lshl_add_u64 v[22:23], v[66:67], 0, v[26:27]
	ds_read_b128 v[18:21], v139
	s_waitcnt vmcnt(15) lgkmcnt(0)
	v_pk_fma_f32 v[20:21], v[194:195], s[98:99], v[20:21] op_sel_hi:[1,0,1]
	v_pk_fma_f32 v[18:19], v[192:193], s[98:99], v[18:19] op_sel_hi:[1,0,1]
	v_lshl_add_u64 v[22:23], v[68:69], 0, v[26:27]
	global_store_dwordx4 v[22:23], v[18:21], off sc0 sc1
	v_lshl_add_u64 v[22:23], v[70:71], 0, v[110:111]
	v_lshlrev_b64 v[26:27], 2, v[22:23]
	v_lshl_add_u64 v[22:23], v[66:67], 0, v[26:27]
	ds_read_b128 v[18:21], v140
	s_waitcnt vmcnt(15) lgkmcnt(0)
	v_pk_fma_f32 v[20:21], v[198:199], s[98:99], v[20:21] op_sel_hi:[1,0,1]
	v_pk_fma_f32 v[18:19], v[196:197], s[98:99], v[18:19] op_sel_hi:[1,0,1]
	v_lshl_add_u64 v[22:23], v[68:69], 0, v[26:27]
	global_store_dwordx4 v[22:23], v[18:21], off sc0 sc1
	s_waitcnt lgkmcnt(0)
	ds_write2_b32 v136, v14, v10 offset1:16
	v_mul_f32_e32 v10, v15, v0
	ds_write2_b32 v50, v6, v2 offset0:64 offset1:80
	v_mul_f32_e32 v2, v7, v0
	ds_write2_b32 v136, v10, v11 offset0:36 offset1:52
	v_mul_f32_e32 v10, v16, v0
	v_mul_f32_e32 v11, v12, v72
	ds_write2_b32 v50, v2, v3 offset0:100 offset1:116
	v_mul_f32_e32 v2, v8, v0
	v_mul_f32_e32 v3, v4, v72
	ds_write2_b32 v136, v10, v11 offset0:72 offset1:88
	v_mul_f32_e32 v10, v17, v0
	v_mul_f32_e32 v11, v13, v72
	ds_write2_b32 v50, v2, v3 offset0:136 offset1:152
	v_mul_f32_e32 v0, v9, v0
	v_mul_f32_e32 v2, v5, v72
	v_lshl_add_u64 v[6:7], v[70:71], 0, v[112:113]
	ds_write2_b32 v136, v10, v11 offset0:108 offset1:124
	ds_write2_b32 v50, v0, v2 offset0:172 offset1:188
	v_lshlrev_b64 v[10:11], 2, v[6:7]
	s_waitcnt lgkmcnt(0)
	v_lshl_add_u64 v[6:7], v[66:67], 0, v[10:11]
	ds_read_b128 v[2:5], v137
	s_waitcnt vmcnt(15) lgkmcnt(0)
	v_pk_fma_f32 v[4:5], v[202:203], s[98:99], v[4:5] op_sel_hi:[1,0,1]
	v_pk_fma_f32 v[2:3], v[200:201], s[98:99], v[2:3] op_sel_hi:[1,0,1]
	v_lshl_add_u64 v[6:7], v[68:69], 0, v[10:11]
	global_store_dwordx4 v[6:7], v[2:5], off sc0 sc1
	v_lshl_add_u64 v[6:7], v[70:71], 0, v[114:115]
	v_lshlrev_b64 v[10:11], 2, v[6:7]
	v_lshl_add_u64 v[6:7], v[66:67], 0, v[10:11]
	ds_read_b128 v[2:5], v138
	s_waitcnt vmcnt(15) lgkmcnt(0)
	v_pk_fma_f32 v[4:5], v[206:207], s[98:99], v[4:5] op_sel_hi:[1,0,1]
	v_pk_fma_f32 v[2:3], v[204:205], s[98:99], v[2:3] op_sel_hi:[1,0,1]
	v_lshl_add_u64 v[6:7], v[68:69], 0, v[10:11]
	global_store_dwordx4 v[6:7], v[2:5], off sc0 sc1
	v_lshl_add_u64 v[6:7], v[70:71], 0, v[116:117]
	v_lshlrev_b64 v[10:11], 2, v[6:7]
	v_lshl_add_u64 v[6:7], v[66:67], 0, v[10:11]
	ds_read_b128 v[2:5], v139
	s_waitcnt vmcnt(15) lgkmcnt(0)
	v_pk_fma_f32 v[4:5], v[210:211], s[98:99], v[4:5] op_sel_hi:[1,0,1]
	v_pk_fma_f32 v[2:3], v[208:209], s[98:99], v[2:3] op_sel_hi:[1,0,1]
	v_lshl_add_u64 v[6:7], v[68:69], 0, v[10:11]
	global_store_dwordx4 v[6:7], v[2:5], off sc0 sc1
	v_lshl_add_u64 v[6:7], v[70:71], 0, v[118:119]
	v_lshlrev_b64 v[10:11], 2, v[6:7]
	v_lshl_add_u64 v[6:7], v[66:67], 0, v[10:11]
	ds_read_b128 v[2:5], v140
	s_waitcnt vmcnt(15) lgkmcnt(0)
	v_pk_fma_f32 v[4:5], v[76:77], s[98:99], v[4:5] op_sel_hi:[1,0,1]
	v_pk_fma_f32 v[2:3], v[74:75], s[98:99], v[2:3] op_sel_hi:[1,0,1]
	v_lshl_add_u64 v[6:7], v[68:69], 0, v[10:11]
	global_store_dwordx4 v[6:7], v[2:5], off sc0 sc1
	s_waitcnt lgkmcnt(0)
	s_cbranch_vccnz .LBB0_45
